# E-GEMM workgroups: idle waves prefetch the Y-GEMM weight slice and GLU weights into L2 during the serial carry scan
# baseline (speedup 1.0000x reference)
; #define LAS __attribute__((address_space(3)))
;     __device__ __forceinline__ void fused(const Acc& acc, const Unit& u, int wr, int wc, int fr, int fq, LAS unsigned char* lds, int wid, int lane) const {
;     ...
; #pragma unroll
;         for (int ai = 0; ai < 2; ++ai)
; #pragma unroll
;             for (int m = 0; m < 4; ++m)
; #pragma unroll
;                 for (int n = 0; n < 2; ++n) { const int r = ai * 128 + wr * 64 + m * 16 + fr, c = wc * 32 + n * 16 + fq * 4; *(LAS f32x4*)(Es + r * 128 + c) = acc[ai][0][m][n]; }
;         __syncthreads();
;         if (wid == 0) {
;             const int g = u.z, b = u.pm, p = lane;
;             const float ar = apow[((g * 17 + 16) * 64 + p) * 2], aim = apow[((g * 17 + 16) * 64 + p) * 2 + 1];
;             float hr = 0.f, hi = 0.f;
;             bf16_t* zp = ZUT + ((size_t)g * NCHUNK + (size_t)b * 256) * KY + 256 + p;
;             float er = Es[p], ei = Es[64 + p];
.LBB0_921:
	s_lshl_b32 s0, s28, 7
	s_add_i32 s0, s0, 0
	s_lshl_b32 s1, s20, 15
	v_and_b32_e32 v66, -16, v64
	v_lshlrev_b32_e32 v65, 9, v65
	s_add_i32 s1, s1, s0
	v_add3_u32 v65, s1, v66, v65
	s_barrier
	ds_write_b128 v65, v[60:63]
	ds_write_b128 v65, v[56:59] offset:64
	ds_write_b128 v65, v[52:55] offset:8192
	ds_write_b128 v65, v[48:51] offset:8256
	ds_write_b128 v65, v[44:47] offset:16384
	ds_write_b128 v65, v[40:43] offset:16448
	ds_write_b128 v65, v[36:39] offset:24576
	ds_write_b128 v65, v[32:35] offset:24640
	v_add_u32_e32 v32, 0x10000, v65
	ds_write_b128 v32, v[28:31]
	ds_write_b128 v32, v[24:27] offset:64
	v_add_u32_e32 v24, 0x12000, v65
	ds_write_b128 v24, v[20:23]
	ds_write_b128 v24, v[16:19] offset:64
	v_add_u32_e32 v16, 0x14000, v65
	ds_write_b128 v16, v[12:15]
	ds_write_b128 v16, v[8:11] offset:64
	v_add_u32_e32 v8, 0x16000, v65
	s_cmp_lg_u32 s19, 0
	s_movk_i32 s24, 0x7e
	ds_write_b128 v8, v[4:7]
	ds_write_b128 v8, v[0:3] offset:64
	s_waitcnt vmcnt(0) lgkmcnt(0)
	s_barrier
	s_cbranch_scc0 .Lmy_epf_scan
	v_mov_b32_e32 v0, 0x20518
	ds_read_b64 v[0:1], v0
	v_mbcnt_lo_u32_b32 v2, -1, 0
	v_mbcnt_hi_u32_b32 v2, -1, v2
	v_lshlrev_b32_e32 v2, 7, v2
	s_lshr_b32 s0, s14, 2
	s_mul_i32 s0, s0, 0x30000
	s_mul_i32 s1, s96, 0x300000
	s_add_i32 s0, s0, s1
	s_add_i32 s0, s0, 0x1c00000
	s_lshl_b32 s20, s96, 17
	s_add_i32 s20, s20, 0x1600000
	s_add_i32 s1, s19, -1
	s_lshl_b32 s1, s1, 13
	v_add_u32_e32 v2, s1, v2
	v_add_u32_e32 v4, 0xe000, v2
	v_add_u32_e32 v5, 0x1c000, v2
	v_add_u32_e32 v6, 0x2a000, v2
	s_waitcnt lgkmcnt(0)
	v_readfirstlane_b32 s2, v0
	v_readfirstlane_b32 s3, v1
	s_nop 3
	s_add_u32 s20, s2, s20
	s_addc_u32 s21, s3, 0
	s_add_u32 s2, s2, s0
	s_addc_u32 s3, s3, 0
	global_load_dword v3, v2, s[2:3]
	global_load_dword v3, v4, s[2:3]
	global_load_dword v3, v5, s[2:3]
	global_load_dword v3, v6, s[2:3]
	global_load_dword v3, v2, s[20:21]
	global_load_dword v3, v4, s[20:21]
	global_load_dword v3, v5, s[20:21]
	s_branch .LBB0_925
.Lmy_epf_scan:
	s_mul_i32 s2, s74, 0x440
	s_mul_i32 s0, s96, 0x22000
	v_readlane_b32 s6, v253, 13
	v_add_u32_e32 v0, s2, v64
	s_mul_hi_u32 s1, s96, 0x22000
	v_readlane_b32 s7, v253, 14
	s_add_u32 s0, s6, s0
	v_lshl_add_u32 v0, v0, 1, v204
	s_addc_u32 s1, s7, s1
	v_ashrrev_i32_e32 v1, 31, v0
	v_lshl_add_u64 v[0:1], v[0:1], 2, s[0:1]
	s_mov_b32 s0, 0x400000
	v_add_co_u32_e32 v0, vcc, s0, v0
	s_add_u32 s1, s17, s18
	s_nop 0
	v_addc_co_u32_e32 v1, vcc, 0, v1, vcc
	global_load_dwordx2 v[0:1], v[0:1], off
	s_addc_u32 s5, s16, 0
	s_add_u32 s4, s6, s1
	v_ashrrev_i32_e32 v65, 31, v64
	s_addc_u32 s5, s7, s5
	v_mov_b32_e32 v6, 0
	s_mov_b64 s[2:3], 0x11d00880
	v_lshl_add_u64 v[2:3], v[64:65], 1, s[4:5]
	s_mov_b32 s0, 0
	v_lshl_add_u32 v8, v64, 2, 0
	v_lshl_add_u64 v[2:3], v[2:3], 0, s[2:3]
	v_mov_b32_e32 v7, v6
	s_waitcnt vmcnt(0)
	v_pk_mov_b32 v[4:5], v[0:1], v[0:1] op_sel:[1,0]
